# input-projection GEMM phase: co-resident block start stagger halved (s_sleep 11)
# speedup vs baseline: 1.0050x; 1.0050x over previous
.LBB0_277:
	s_or_b64 exec, exec, s[0:1]
	s_and_b32 s0, s33, 1
	s_bitcmp1_b32 s33, 0
	s_cselect_b64 s[2:3], -1, 0
	v_writelane_b32 v246, s2, 26
	s_cmp_eq_u32 s0, 0
	s_waitcnt lgkmcnt(0)
	s_barrier
	v_writelane_b32 v246, s3, 27
	s_cbranch_scc1 .LBB0_279
	s_sleep 11
